# after the P2 seam the workgroups of odd XCDs start 20 us later, so the two halves' bandwidth-bound epilogues interleave with the other half's matrix-core main loops
# baseline (speedup 1.0000x reference)
.LBB0_662:
	s_or_b64 exec, exec, s[0:1]
	v_mov_b32_e32 v8, v176
	v_readlane_b32 s40, v252, 13
	s_bitcmp1_b32 s40, 0
	s_cbranch_scc0 .Lstag_skip
	s_memrealtime s[40:41]
	s_waitcnt lgkmcnt(0)
.Lstag_wait:
	s_memrealtime s[42:43]
	s_waitcnt lgkmcnt(0)
	s_sub_u32 s44, s42, s40
	s_cmp_lt_u32 s44, 2000
	s_cbranch_scc1 .Lstag_wait
.Lstag_skip:
	s_cmpk_lt_i32 s72, 0x100
	s_waitcnt lgkmcnt(0)
	s_barrier
	s_cselect_b64 s[0:1], -1, 0
	s_cmpk_gt_i32 s72, 0xff
	v_readfirstlane_b32 s10, v8
	s_cbranch_scc1 .LBB0_686
	s_ashr_i32 s2, s72, 31
	s_lshr_b32 s3, s2, 29
	s_add_i32 s3, s72, s3
	s_and_b32 s4, s3, -8
	s_sub_i32 s7, s72, s4
	s_cmp_gt_i32 s7, -1
	s_cbranch_scc0 .LBB0_665
	s_lshl_b32 s6, s7, 5
	s_cbranch_execz .LBB0_666
	s_branch .LBB0_667
